# grid barrier leader path: drop the unused per-XCD generation update and the vmcnt(0) waits behind fire-and-forget generation atomics
# speedup vs baseline: 1.0011x; 1.0011x over previous
.LBB0_2068:
	s_or_b64 exec, exec, s[2:3]
	buffer_inv sc1
